# attention: cmp head-sum shuffles via DPP instead of ds_bpermute; top-k rank count software-pipelined (cmp results consumed 2+ slots later, no s_nop pads, all 16 key quads read up front)
# speedup vs baseline: 1.0266x; 1.0113x over previous
.LBB0_1098:
	ds_bpermute_b32 v35, v209, v40
	v_and_b32_e32 v228, 24, v38
	v_lshlrev_b32_e32 v37, 1, v37
	v_and_or_b32 v39, v39, 3, v210
	v_and_b32_e32 v229, 32, v37
	s_waitcnt lgkmcnt(0)
	v_add_f32_e32 v35, v40, v35
	v_max_f32_e32 v35, 0xda24260, v35
	v_div_scale_f32 v40, s[8:9], v35, v35, 1.0
	v_rcp_f32_e32 v41, v40
	v_lshlrev_b32_e32 v37, 6, v39
	v_fma_f32 v38, -v40, v41, 1.0
	v_fmac_f32_e32 v41, v38, v41
	v_div_scale_f32 v38, vcc, 1.0, v35, 1.0
	v_mul_f32_e32 v39, v38, v41
	v_fma_f32 v42, -v40, v39, v38
	v_fmac_f32_e32 v39, v42, v41
	v_fma_f32 v38, -v40, v39, v38
	v_div_fmas_f32 v38, v38, v41, v39
	v_div_fixup_f32 v190, v38, v35, 1.0
	v_add_u32_e32 v35, 0, v229
	v_add3_u32 v230, v35, v228, v37
	v_lshlrev_b32_e32 v35, 10, v226
	v_lshlrev_b32_e32 v37, 2, v210
	v_add3_u32 v231, s76, v35, v37
	v_xor_b32_e32 v35, 1, v179
	v_cmp_lt_i32_e32 vcc, v35, v34
	s_nop 1
	v_cndmask_b32_e32 v35, v179, v35, vcc
	v_lshlrev_b32_e32 v233, 2, v35
	v_xor_b32_e32 v35, 2, v179
	v_cmp_lt_i32_e32 vcc, v35, v34
	s_nop 1
	v_cndmask_b32_e32 v34, v179, v35, vcc
	v_lshlrev_b32_e32 v232, 2, v34
	s_and_b64 vcc, exec, s[0:1]
	v_cmp_eq_u32_e64 s[0:1], 0, v36
	s_cbranch_vccnz .LBB0_1127
	v_pk_mul_f32 v[34:35], v[18:19], v[190:191] op_sel_hi:[1,0]
	v_pk_mul_f32 v[192:193], v[2:3], v[190:191] op_sel_hi:[1,0]
	v_pk_mul_f32 v[36:37], v[20:21], v[190:191] op_sel_hi:[1,0]
	v_pk_mul_f32 v[194:195], v[4:5], v[190:191] op_sel_hi:[1,0]
	v_mov_b32_dpp v38, v34 quad_perm:[1,0,3,2] row_mask:0xf bank_mask:0xf
	v_mov_b32_dpp v39, v35 quad_perm:[1,0,3,2] row_mask:0xf bank_mask:0xf
	v_mov_b32_dpp v40, v36 quad_perm:[1,0,3,2] row_mask:0xf bank_mask:0xf
	v_mov_b32_dpp v41, v37 quad_perm:[1,0,3,2] row_mask:0xf bank_mask:0xf
	v_mov_b32_dpp v42, v192 quad_perm:[1,0,3,2] row_mask:0xf bank_mask:0xf
	v_mov_b32_dpp v43, v193 quad_perm:[1,0,3,2] row_mask:0xf bank_mask:0xf
	v_mov_b32_dpp v44, v194 quad_perm:[1,0,3,2] row_mask:0xf bank_mask:0xf
	v_mov_b32_dpp v45, v195 quad_perm:[1,0,3,2] row_mask:0xf bank_mask:0xf
	s_waitcnt lgkmcnt(6)
	v_pk_fma_f32 v[18:19], v[18:19], v[190:191], v[38:39] op_sel_hi:[1,0,1]
	s_waitcnt lgkmcnt(4)
	v_pk_fma_f32 v[20:21], v[20:21], v[190:191], v[40:41] op_sel_hi:[1,0,1]
	s_waitcnt lgkmcnt(2)
	v_pk_fma_f32 v[2:3], v[2:3], v[190:191], v[42:43] op_sel_hi:[1,0,1]
	v_mov_b32_dpp v38, v18 quad_perm:[2,3,0,1] row_mask:0xf bank_mask:0xf
	s_waitcnt lgkmcnt(1)
	v_pk_fma_f32 v[4:5], v[4:5], v[190:191], v[44:45] op_sel_hi:[1,0,1]
	v_mov_b32_dpp v39, v19 quad_perm:[2,3,0,1] row_mask:0xf bank_mask:0xf
	v_mov_b32_dpp v40, v20 quad_perm:[2,3,0,1] row_mask:0xf bank_mask:0xf
	v_mov_b32_dpp v41, v21 quad_perm:[2,3,0,1] row_mask:0xf bank_mask:0xf
	v_mov_b32_dpp v42, v2 quad_perm:[2,3,0,1] row_mask:0xf bank_mask:0xf
	v_mov_b32_dpp v43, v3 quad_perm:[2,3,0,1] row_mask:0xf bank_mask:0xf
	v_mov_b32_dpp v44, v4 quad_perm:[2,3,0,1] row_mask:0xf bank_mask:0xf
	v_mov_b32_dpp v45, v5 quad_perm:[2,3,0,1] row_mask:0xf bank_mask:0xf
	s_and_saveexec_b64 s[8:9], s[0:1]
	s_cbranch_execz .LBB0_1101
	s_waitcnt lgkmcnt(6)
	v_pk_add_f32 v[18:19], v[18:19], v[38:39]
	s_waitcnt lgkmcnt(4)
	v_pk_add_f32 v[20:21], v[20:21], v[40:41]
	s_waitcnt lgkmcnt(2)
	v_pk_add_f32 v[2:3], v[2:3], v[42:43]
	s_waitcnt lgkmcnt(0)
	v_pk_add_f32 v[4:5], v[4:5], v[44:45]
	ds_write_b128 v231, v[18:21]
	ds_write_b128 v231, v[2:5] offset:128
.LBB0_1101:
	s_or_b64 exec, exec, s[8:9]
	v_mov_b32_e32 v191, v190
	v_pk_mul_f32 v[18:19], v[22:23], v[190:191]
	v_pk_mul_f32 v[2:3], v[6:7], v[190:191]
	v_pk_mul_f32 v[20:21], v[24:25], v[190:191]
	v_pk_mul_f32 v[4:5], v[8:9], v[190:191]
	s_waitcnt lgkmcnt(7)
	v_mov_b32_dpp v38, v18 quad_perm:[1,0,3,2] row_mask:0xf bank_mask:0xf
	s_waitcnt lgkmcnt(7)
	v_mov_b32_dpp v39, v19 quad_perm:[1,0,3,2] row_mask:0xf bank_mask:0xf
	s_waitcnt lgkmcnt(7)
	v_mov_b32_dpp v40, v20 quad_perm:[1,0,3,2] row_mask:0xf bank_mask:0xf
	s_waitcnt lgkmcnt(7)
	v_mov_b32_dpp v41, v21 quad_perm:[1,0,3,2] row_mask:0xf bank_mask:0xf
	s_waitcnt lgkmcnt(7)
	v_mov_b32_dpp v42, v2 quad_perm:[1,0,3,2] row_mask:0xf bank_mask:0xf
	s_waitcnt lgkmcnt(7)
	v_mov_b32_dpp v43, v3 quad_perm:[1,0,3,2] row_mask:0xf bank_mask:0xf
	s_waitcnt lgkmcnt(7)
	v_mov_b32_dpp v44, v4 quad_perm:[1,0,3,2] row_mask:0xf bank_mask:0xf
	s_waitcnt lgkmcnt(7)
	v_mov_b32_dpp v45, v5 quad_perm:[1,0,3,2] row_mask:0xf bank_mask:0xf
	s_waitcnt lgkmcnt(6)
	v_pk_fma_f32 v[22:23], v[22:23], v[190:191], v[38:39]
	s_waitcnt lgkmcnt(4)
	v_pk_fma_f32 v[24:25], v[24:25], v[190:191], v[40:41]
	s_waitcnt lgkmcnt(2)
	v_pk_fma_f32 v[6:7], v[6:7], v[190:191], v[42:43]
	v_mov_b32_dpp v38, v22 quad_perm:[2,3,0,1] row_mask:0xf bank_mask:0xf
	s_waitcnt lgkmcnt(1)
	v_pk_fma_f32 v[8:9], v[8:9], v[190:191], v[44:45]
	v_mov_b32_dpp v39, v23 quad_perm:[2,3,0,1] row_mask:0xf bank_mask:0xf
	v_mov_b32_dpp v40, v24 quad_perm:[2,3,0,1] row_mask:0xf bank_mask:0xf
	v_mov_b32_dpp v41, v25 quad_perm:[2,3,0,1] row_mask:0xf bank_mask:0xf
	v_mov_b32_dpp v42, v6 quad_perm:[2,3,0,1] row_mask:0xf bank_mask:0xf
	v_mov_b32_dpp v43, v7 quad_perm:[2,3,0,1] row_mask:0xf bank_mask:0xf
	v_mov_b32_dpp v44, v8 quad_perm:[2,3,0,1] row_mask:0xf bank_mask:0xf
	v_mov_b32_dpp v45, v9 quad_perm:[2,3,0,1] row_mask:0xf bank_mask:0xf
	s_and_saveexec_b64 s[8:9], s[0:1]
	s_cbranch_execz .LBB0_1103
	s_waitcnt lgkmcnt(6)
	v_pk_add_f32 v[22:23], v[22:23], v[38:39]
	s_waitcnt lgkmcnt(4)
	v_pk_add_f32 v[24:25], v[24:25], v[40:41]
	s_waitcnt lgkmcnt(2)
	v_pk_add_f32 v[6:7], v[6:7], v[42:43]
	s_waitcnt lgkmcnt(0)
	v_pk_add_f32 v[8:9], v[8:9], v[44:45]
	ds_write_b128 v231, v[22:25] offset:32
	ds_write_b128 v231, v[6:9] offset:160
.LBB0_1103:
	s_or_b64 exec, exec, s[8:9]
	v_pk_mul_f32 v[22:23], v[26:27], v[190:191]
	v_pk_mul_f32 v[6:7], v[10:11], v[190:191]
	v_pk_mul_f32 v[24:25], v[28:29], v[190:191]
	v_pk_mul_f32 v[8:9], v[12:13], v[190:191]
	s_waitcnt lgkmcnt(7)
	v_mov_b32_dpp v38, v22 quad_perm:[1,0,3,2] row_mask:0xf bank_mask:0xf
	s_waitcnt lgkmcnt(7)
	v_mov_b32_dpp v39, v23 quad_perm:[1,0,3,2] row_mask:0xf bank_mask:0xf
	s_waitcnt lgkmcnt(7)
	v_mov_b32_dpp v40, v24 quad_perm:[1,0,3,2] row_mask:0xf bank_mask:0xf
	s_waitcnt lgkmcnt(7)
	v_mov_b32_dpp v41, v25 quad_perm:[1,0,3,2] row_mask:0xf bank_mask:0xf
	s_waitcnt lgkmcnt(7)
	v_mov_b32_dpp v42, v6 quad_perm:[1,0,3,2] row_mask:0xf bank_mask:0xf
	s_waitcnt lgkmcnt(7)
	v_mov_b32_dpp v43, v7 quad_perm:[1,0,3,2] row_mask:0xf bank_mask:0xf
	s_waitcnt lgkmcnt(7)
	v_mov_b32_dpp v44, v8 quad_perm:[1,0,3,2] row_mask:0xf bank_mask:0xf
	s_waitcnt lgkmcnt(7)
	v_mov_b32_dpp v45, v9 quad_perm:[1,0,3,2] row_mask:0xf bank_mask:0xf
	s_waitcnt lgkmcnt(6)
	v_pk_fma_f32 v[26:27], v[26:27], v[190:191], v[38:39]
	s_waitcnt lgkmcnt(4)
	v_pk_fma_f32 v[28:29], v[28:29], v[190:191], v[40:41]
	s_waitcnt lgkmcnt(2)
	v_pk_fma_f32 v[10:11], v[10:11], v[190:191], v[42:43]
	v_mov_b32_dpp v38, v26 quad_perm:[2,3,0,1] row_mask:0xf bank_mask:0xf
	s_waitcnt lgkmcnt(1)
	v_pk_fma_f32 v[12:13], v[12:13], v[190:191], v[44:45]
	v_mov_b32_dpp v39, v27 quad_perm:[2,3,0,1] row_mask:0xf bank_mask:0xf
	v_mov_b32_dpp v40, v28 quad_perm:[2,3,0,1] row_mask:0xf bank_mask:0xf
	v_mov_b32_dpp v41, v29 quad_perm:[2,3,0,1] row_mask:0xf bank_mask:0xf
	v_mov_b32_dpp v42, v10 quad_perm:[2,3,0,1] row_mask:0xf bank_mask:0xf
	v_mov_b32_dpp v43, v11 quad_perm:[2,3,0,1] row_mask:0xf bank_mask:0xf
	v_mov_b32_dpp v44, v12 quad_perm:[2,3,0,1] row_mask:0xf bank_mask:0xf
	v_mov_b32_dpp v45, v13 quad_perm:[2,3,0,1] row_mask:0xf bank_mask:0xf
	s_and_saveexec_b64 s[8:9], s[0:1]
	s_cbranch_execz .LBB0_1105
	s_waitcnt lgkmcnt(6)
	v_pk_add_f32 v[26:27], v[26:27], v[38:39]
	s_waitcnt lgkmcnt(4)
	v_pk_add_f32 v[28:29], v[28:29], v[40:41]
	s_waitcnt lgkmcnt(2)
	v_pk_add_f32 v[10:11], v[10:11], v[42:43]
	s_waitcnt lgkmcnt(0)
	v_pk_add_f32 v[12:13], v[12:13], v[44:45]
	ds_write_b128 v231, v[26:29] offset:64
	ds_write_b128 v231, v[10:13] offset:192
.LBB0_1105:
	s_or_b64 exec, exec, s[8:9]
	v_pk_mul_f32 v[26:27], v[30:31], v[190:191]
	v_pk_mul_f32 v[10:11], v[14:15], v[190:191]
	v_pk_mul_f32 v[28:29], v[32:33], v[190:191]
	v_pk_mul_f32 v[12:13], v[16:17], v[190:191]
	s_waitcnt lgkmcnt(7)
	v_mov_b32_dpp v38, v26 quad_perm:[1,0,3,2] row_mask:0xf bank_mask:0xf
	s_waitcnt lgkmcnt(7)
	v_mov_b32_dpp v39, v27 quad_perm:[1,0,3,2] row_mask:0xf bank_mask:0xf
	s_waitcnt lgkmcnt(7)
	v_mov_b32_dpp v40, v28 quad_perm:[1,0,3,2] row_mask:0xf bank_mask:0xf
	s_waitcnt lgkmcnt(7)
	v_mov_b32_dpp v41, v29 quad_perm:[1,0,3,2] row_mask:0xf bank_mask:0xf
	s_waitcnt lgkmcnt(7)
	v_mov_b32_dpp v42, v10 quad_perm:[1,0,3,2] row_mask:0xf bank_mask:0xf
	s_waitcnt lgkmcnt(7)
	v_mov_b32_dpp v43, v11 quad_perm:[1,0,3,2] row_mask:0xf bank_mask:0xf
	s_waitcnt lgkmcnt(7)
	v_mov_b32_dpp v44, v12 quad_perm:[1,0,3,2] row_mask:0xf bank_mask:0xf
	s_waitcnt lgkmcnt(7)
	v_mov_b32_dpp v45, v13 quad_perm:[1,0,3,2] row_mask:0xf bank_mask:0xf
	s_waitcnt lgkmcnt(6)
	v_pk_fma_f32 v[30:31], v[30:31], v[190:191], v[38:39]
	s_waitcnt lgkmcnt(4)
	v_pk_fma_f32 v[32:33], v[32:33], v[190:191], v[40:41]
	s_waitcnt lgkmcnt(2)
	v_pk_fma_f32 v[14:15], v[14:15], v[190:191], v[42:43]
	v_mov_b32_dpp v38, v30 quad_perm:[2,3,0,1] row_mask:0xf bank_mask:0xf
	s_waitcnt lgkmcnt(1)
	v_pk_fma_f32 v[16:17], v[16:17], v[190:191], v[44:45]
	v_mov_b32_dpp v39, v31 quad_perm:[2,3,0,1] row_mask:0xf bank_mask:0xf
	v_mov_b32_dpp v40, v32 quad_perm:[2,3,0,1] row_mask:0xf bank_mask:0xf
	v_mov_b32_dpp v41, v33 quad_perm:[2,3,0,1] row_mask:0xf bank_mask:0xf
	v_mov_b32_dpp v42, v14 quad_perm:[2,3,0,1] row_mask:0xf bank_mask:0xf
	v_mov_b32_dpp v43, v15 quad_perm:[2,3,0,1] row_mask:0xf bank_mask:0xf
	v_mov_b32_dpp v44, v16 quad_perm:[2,3,0,1] row_mask:0xf bank_mask:0xf
	v_mov_b32_dpp v45, v17 quad_perm:[2,3,0,1] row_mask:0xf bank_mask:0xf
	s_and_saveexec_b64 s[8:9], s[0:1]
	s_cbranch_execz .LBB0_1107
	s_waitcnt lgkmcnt(6)
	v_pk_add_f32 v[30:31], v[30:31], v[38:39]
	s_waitcnt lgkmcnt(4)
	v_pk_add_f32 v[32:33], v[32:33], v[40:41]
	s_waitcnt lgkmcnt(2)
	v_pk_add_f32 v[14:15], v[14:15], v[42:43]
	s_waitcnt lgkmcnt(0)
	v_pk_add_f32 v[16:17], v[16:17], v[44:45]
	ds_write_b128 v231, v[30:33] offset:96
	ds_write_b128 v231, v[14:17] offset:224

.LBB0_1108:
	v_pk_mul_f32 v[38:39], v[146:147], v[190:191] op_sel_hi:[1,0]
	v_pk_mul_f32 v[34:35], v[130:131], v[190:191] op_sel_hi:[1,0]
	v_pk_mul_f32 v[40:41], v[148:149], v[190:191] op_sel_hi:[1,0]
	v_pk_mul_f32 v[36:37], v[132:133], v[190:191] op_sel_hi:[1,0]
	v_mov_b32_dpp v42, v38 quad_perm:[1,0,3,2] row_mask:0xf bank_mask:0xf
	v_mov_b32_dpp v43, v39 quad_perm:[1,0,3,2] row_mask:0xf bank_mask:0xf
	v_mov_b32_dpp v46, v40 quad_perm:[1,0,3,2] row_mask:0xf bank_mask:0xf
	v_mov_b32_dpp v47, v41 quad_perm:[1,0,3,2] row_mask:0xf bank_mask:0xf
	v_mov_b32_dpp v50, v34 quad_perm:[1,0,3,2] row_mask:0xf bank_mask:0xf
	v_mov_b32_dpp v51, v35 quad_perm:[1,0,3,2] row_mask:0xf bank_mask:0xf
	v_mov_b32_dpp v54, v36 quad_perm:[1,0,3,2] row_mask:0xf bank_mask:0xf
	v_mov_b32_dpp v55, v37 quad_perm:[1,0,3,2] row_mask:0xf bank_mask:0xf
	s_waitcnt lgkmcnt(6)
	v_pk_fma_f32 v[42:43], v[146:147], v[190:191], v[42:43] op_sel_hi:[1,0,1]
	s_waitcnt lgkmcnt(4)
	v_pk_fma_f32 v[46:47], v[148:149], v[190:191], v[46:47] op_sel_hi:[1,0,1]
	s_waitcnt lgkmcnt(2)
	v_pk_fma_f32 v[50:51], v[130:131], v[190:191], v[50:51] op_sel_hi:[1,0,1]
	v_mov_b32_dpp v44, v42 quad_perm:[2,3,0,1] row_mask:0xf bank_mask:0xf
	s_waitcnt lgkmcnt(1)
	v_pk_fma_f32 v[54:55], v[132:133], v[190:191], v[54:55] op_sel_hi:[1,0,1]
	v_mov_b32_dpp v45, v43 quad_perm:[2,3,0,1] row_mask:0xf bank_mask:0xf
	v_mov_b32_dpp v48, v46 quad_perm:[2,3,0,1] row_mask:0xf bank_mask:0xf
	v_mov_b32_dpp v49, v47 quad_perm:[2,3,0,1] row_mask:0xf bank_mask:0xf
	v_mov_b32_dpp v52, v50 quad_perm:[2,3,0,1] row_mask:0xf bank_mask:0xf
	v_mov_b32_dpp v53, v51 quad_perm:[2,3,0,1] row_mask:0xf bank_mask:0xf
	v_mov_b32_dpp v56, v54 quad_perm:[2,3,0,1] row_mask:0xf bank_mask:0xf
	v_mov_b32_dpp v57, v55 quad_perm:[2,3,0,1] row_mask:0xf bank_mask:0xf
	s_and_saveexec_b64 s[6:7], s[0:1]
	s_cbranch_execz .LBB0_1110
	s_waitcnt lgkmcnt(6)
	v_pk_add_f32 v[42:43], v[42:43], v[44:45]
	s_waitcnt lgkmcnt(4)
	v_pk_add_f32 v[44:45], v[46:47], v[48:49]
	ds_write_b128 v231, v[42:45] offset:256
	s_waitcnt lgkmcnt(3)
	v_pk_add_f32 v[42:43], v[50:51], v[52:53]
	s_waitcnt lgkmcnt(1)
	v_pk_add_f32 v[44:45], v[54:55], v[56:57]
	ds_write_b128 v231, v[42:45] offset:384
.LBB0_1110:
	s_or_b64 exec, exec, s[6:7]
	v_mov_b32_e32 v191, v190
	s_waitcnt lgkmcnt(4)
	v_pk_mul_f32 v[48:49], v[150:151], v[190:191]
	v_pk_mul_f32 v[42:43], v[134:135], v[190:191]
	s_waitcnt lgkmcnt(2)
	v_pk_mul_f32 v[52:53], v[152:153], v[190:191]
	v_pk_mul_f32 v[44:45], v[136:137], v[190:191]
	v_mov_b32_dpp v46, v48 quad_perm:[1,0,3,2] row_mask:0xf bank_mask:0xf
	v_mov_b32_dpp v47, v49 quad_perm:[1,0,3,2] row_mask:0xf bank_mask:0xf
	v_mov_b32_dpp v54, v52 quad_perm:[1,0,3,2] row_mask:0xf bank_mask:0xf
	v_mov_b32_dpp v55, v53 quad_perm:[1,0,3,2] row_mask:0xf bank_mask:0xf
	v_mov_b32_dpp v58, v42 quad_perm:[1,0,3,2] row_mask:0xf bank_mask:0xf
	v_mov_b32_dpp v59, v43 quad_perm:[1,0,3,2] row_mask:0xf bank_mask:0xf
	v_mov_b32_dpp v62, v44 quad_perm:[1,0,3,2] row_mask:0xf bank_mask:0xf
	v_mov_b32_dpp v63, v45 quad_perm:[1,0,3,2] row_mask:0xf bank_mask:0xf
	s_waitcnt lgkmcnt(6)
	v_pk_fma_f32 v[46:47], v[150:151], v[190:191], v[46:47]
	s_waitcnt lgkmcnt(4)
	v_pk_fma_f32 v[54:55], v[152:153], v[190:191], v[54:55]
	s_waitcnt lgkmcnt(2)
	v_pk_fma_f32 v[58:59], v[134:135], v[190:191], v[58:59]
	v_mov_b32_dpp v50, v46 quad_perm:[2,3,0,1] row_mask:0xf bank_mask:0xf
	s_waitcnt lgkmcnt(1)
	v_pk_fma_f32 v[62:63], v[136:137], v[190:191], v[62:63]
	v_mov_b32_dpp v51, v47 quad_perm:[2,3,0,1] row_mask:0xf bank_mask:0xf
	v_mov_b32_dpp v56, v54 quad_perm:[2,3,0,1] row_mask:0xf bank_mask:0xf
	v_mov_b32_dpp v57, v55 quad_perm:[2,3,0,1] row_mask:0xf bank_mask:0xf
	v_mov_b32_dpp v60, v58 quad_perm:[2,3,0,1] row_mask:0xf bank_mask:0xf
	v_mov_b32_dpp v61, v59 quad_perm:[2,3,0,1] row_mask:0xf bank_mask:0xf
	v_mov_b32_dpp v64, v62 quad_perm:[2,3,0,1] row_mask:0xf bank_mask:0xf
	v_mov_b32_dpp v65, v63 quad_perm:[2,3,0,1] row_mask:0xf bank_mask:0xf
	s_and_saveexec_b64 s[6:7], s[0:1]
	s_cbranch_execz .LBB0_1112
	s_waitcnt lgkmcnt(6)
	v_pk_add_f32 v[130:131], v[46:47], v[50:51]
	s_waitcnt lgkmcnt(4)
	v_pk_add_f32 v[132:133], v[54:55], v[56:57]
	s_waitcnt lgkmcnt(2)
	v_pk_add_f32 v[54:55], v[58:59], v[60:61]
	s_waitcnt lgkmcnt(0)
	v_pk_add_f32 v[56:57], v[62:63], v[64:65]
	ds_write_b128 v231, v[130:133] offset:288
	ds_write_b128 v231, v[54:57] offset:416
.LBB0_1112:
	s_or_b64 exec, exec, s[6:7]
	v_pk_mul_f32 v[54:55], v[154:155], v[190:191]
	v_pk_mul_f32 v[46:47], v[138:139], v[190:191]
	s_waitcnt lgkmcnt(4)
	v_pk_mul_f32 v[56:57], v[156:157], v[190:191]
	v_pk_mul_f32 v[50:51], v[140:141], v[190:191]
	v_mov_b32_dpp v58, v54 quad_perm:[1,0,3,2] row_mask:0xf bank_mask:0xf
	v_mov_b32_dpp v59, v55 quad_perm:[1,0,3,2] row_mask:0xf bank_mask:0xf
	v_mov_b32_dpp v62, v56 quad_perm:[1,0,3,2] row_mask:0xf bank_mask:0xf
	v_mov_b32_dpp v63, v57 quad_perm:[1,0,3,2] row_mask:0xf bank_mask:0xf
	v_mov_b32_dpp v130, v46 quad_perm:[1,0,3,2] row_mask:0xf bank_mask:0xf
	v_mov_b32_dpp v131, v47 quad_perm:[1,0,3,2] row_mask:0xf bank_mask:0xf
	v_mov_b32_dpp v134, v50 quad_perm:[1,0,3,2] row_mask:0xf bank_mask:0xf
	v_mov_b32_dpp v135, v51 quad_perm:[1,0,3,2] row_mask:0xf bank_mask:0xf
	s_waitcnt lgkmcnt(6)
	v_pk_fma_f32 v[58:59], v[154:155], v[190:191], v[58:59]
	s_waitcnt lgkmcnt(4)
	v_pk_fma_f32 v[62:63], v[156:157], v[190:191], v[62:63]
	s_waitcnt lgkmcnt(2)
	v_pk_fma_f32 v[130:131], v[138:139], v[190:191], v[130:131]
	v_mov_b32_dpp v60, v58 quad_perm:[2,3,0,1] row_mask:0xf bank_mask:0xf
	s_waitcnt lgkmcnt(1)
	v_pk_fma_f32 v[134:135], v[140:141], v[190:191], v[134:135]
	v_mov_b32_dpp v61, v59 quad_perm:[2,3,0,1] row_mask:0xf bank_mask:0xf
	v_mov_b32_dpp v64, v62 quad_perm:[2,3,0,1] row_mask:0xf bank_mask:0xf
	v_mov_b32_dpp v65, v63 quad_perm:[2,3,0,1] row_mask:0xf bank_mask:0xf
	v_mov_b32_dpp v132, v130 quad_perm:[2,3,0,1] row_mask:0xf bank_mask:0xf
	v_mov_b32_dpp v133, v131 quad_perm:[2,3,0,1] row_mask:0xf bank_mask:0xf
	v_mov_b32_dpp v136, v134 quad_perm:[2,3,0,1] row_mask:0xf bank_mask:0xf
	v_mov_b32_dpp v137, v135 quad_perm:[2,3,0,1] row_mask:0xf bank_mask:0xf
	s_and_saveexec_b64 s[6:7], s[0:1]
	s_cbranch_execz .LBB0_1114
	s_waitcnt lgkmcnt(6)
	v_pk_add_f32 v[58:59], v[58:59], v[60:61]
	s_waitcnt lgkmcnt(4)
	v_pk_add_f32 v[60:61], v[62:63], v[64:65]
	ds_write_b128 v231, v[58:61] offset:320
	s_waitcnt lgkmcnt(3)
	v_pk_add_f32 v[58:59], v[130:131], v[132:133]
	s_waitcnt lgkmcnt(1)
	v_pk_add_f32 v[60:61], v[134:135], v[136:137]
	ds_write_b128 v231, v[58:61] offset:448
.LBB0_1114:
	s_or_b64 exec, exec, s[6:7]
	v_pk_mul_f32 v[62:63], v[158:159], v[190:191]
	v_pk_mul_f32 v[58:59], v[142:143], v[190:191]
	s_waitcnt lgkmcnt(4)
	v_pk_mul_f32 v[64:65], v[160:161], v[190:191]
	v_pk_mul_f32 v[60:61], v[144:145], v[190:191]
	v_mov_b32_dpp v130, v62 quad_perm:[1,0,3,2] row_mask:0xf bank_mask:0xf
	v_mov_b32_dpp v131, v63 quad_perm:[1,0,3,2] row_mask:0xf bank_mask:0xf
	v_mov_b32_dpp v134, v64 quad_perm:[1,0,3,2] row_mask:0xf bank_mask:0xf
	v_mov_b32_dpp v135, v65 quad_perm:[1,0,3,2] row_mask:0xf bank_mask:0xf
	v_mov_b32_dpp v138, v58 quad_perm:[1,0,3,2] row_mask:0xf bank_mask:0xf
	v_mov_b32_dpp v139, v59 quad_perm:[1,0,3,2] row_mask:0xf bank_mask:0xf
	v_mov_b32_dpp v146, v60 quad_perm:[1,0,3,2] row_mask:0xf bank_mask:0xf
	v_mov_b32_dpp v147, v61 quad_perm:[1,0,3,2] row_mask:0xf bank_mask:0xf
	s_waitcnt lgkmcnt(6)
	v_pk_fma_f32 v[130:131], v[158:159], v[190:191], v[130:131]
	s_waitcnt lgkmcnt(4)
	v_pk_fma_f32 v[134:135], v[160:161], v[190:191], v[134:135]
	s_waitcnt lgkmcnt(2)
	v_pk_fma_f32 v[138:139], v[142:143], v[190:191], v[138:139]
	v_mov_b32_dpp v132, v130 quad_perm:[2,3,0,1] row_mask:0xf bank_mask:0xf
	s_waitcnt lgkmcnt(1)
	v_pk_fma_f32 v[142:143], v[144:145], v[190:191], v[146:147]
	v_mov_b32_dpp v133, v131 quad_perm:[2,3,0,1] row_mask:0xf bank_mask:0xf
	v_mov_b32_dpp v136, v134 quad_perm:[2,3,0,1] row_mask:0xf bank_mask:0xf
	v_mov_b32_dpp v137, v135 quad_perm:[2,3,0,1] row_mask:0xf bank_mask:0xf
	v_mov_b32_dpp v140, v138 quad_perm:[2,3,0,1] row_mask:0xf bank_mask:0xf
	v_mov_b32_dpp v141, v139 quad_perm:[2,3,0,1] row_mask:0xf bank_mask:0xf
	v_mov_b32_dpp v144, v142 quad_perm:[2,3,0,1] row_mask:0xf bank_mask:0xf
	v_mov_b32_dpp v145, v143 quad_perm:[2,3,0,1] row_mask:0xf bank_mask:0xf
	s_and_saveexec_b64 s[6:7], s[0:1]
	s_cbranch_execz .LBB0_1116
	s_waitcnt lgkmcnt(6)
	v_pk_add_f32 v[130:131], v[130:131], v[132:133]
	s_waitcnt lgkmcnt(4)
	v_pk_add_f32 v[132:133], v[134:135], v[136:137]
	ds_write_b128 v231, v[130:133] offset:352
	s_waitcnt lgkmcnt(3)
	v_pk_add_f32 v[130:131], v[138:139], v[140:141]
	s_waitcnt lgkmcnt(1)
	v_pk_add_f32 v[132:133], v[142:143], v[144:145]
	ds_write_b128 v231, v[130:133] offset:480

.LBB0_1117:
	v_pk_mul_f32 v[40:41], v[114:115], v[190:191] op_sel_hi:[1,0]
	v_pk_mul_f32 v[34:35], v[98:99], v[190:191] op_sel_hi:[1,0]
	v_pk_mul_f32 v[44:45], v[116:117], v[190:191] op_sel_hi:[1,0]
	v_pk_mul_f32 v[36:37], v[100:101], v[190:191] op_sel_hi:[1,0]
	v_mov_b32_dpp v38, v40 quad_perm:[1,0,3,2] row_mask:0xf bank_mask:0xf
	v_mov_b32_dpp v39, v41 quad_perm:[1,0,3,2] row_mask:0xf bank_mask:0xf
	v_mov_b32_dpp v46, v44 quad_perm:[1,0,3,2] row_mask:0xf bank_mask:0xf
	v_mov_b32_dpp v47, v45 quad_perm:[1,0,3,2] row_mask:0xf bank_mask:0xf
	v_mov_b32_dpp v50, v34 quad_perm:[1,0,3,2] row_mask:0xf bank_mask:0xf
	v_mov_b32_dpp v51, v35 quad_perm:[1,0,3,2] row_mask:0xf bank_mask:0xf
	v_mov_b32_dpp v54, v36 quad_perm:[1,0,3,2] row_mask:0xf bank_mask:0xf
	v_mov_b32_dpp v55, v37 quad_perm:[1,0,3,2] row_mask:0xf bank_mask:0xf
	s_waitcnt lgkmcnt(6)
	v_pk_fma_f32 v[38:39], v[114:115], v[190:191], v[38:39] op_sel_hi:[1,0,1]
	s_waitcnt lgkmcnt(4)
	v_pk_fma_f32 v[46:47], v[116:117], v[190:191], v[46:47] op_sel_hi:[1,0,1]
	s_waitcnt lgkmcnt(2)
	v_pk_fma_f32 v[50:51], v[98:99], v[190:191], v[50:51] op_sel_hi:[1,0,1]
	v_mov_b32_dpp v42, v38 quad_perm:[2,3,0,1] row_mask:0xf bank_mask:0xf
	s_waitcnt lgkmcnt(1)
	v_pk_fma_f32 v[54:55], v[100:101], v[190:191], v[54:55] op_sel_hi:[1,0,1]
	v_mov_b32_dpp v43, v39 quad_perm:[2,3,0,1] row_mask:0xf bank_mask:0xf
	v_mov_b32_dpp v48, v46 quad_perm:[2,3,0,1] row_mask:0xf bank_mask:0xf
	v_mov_b32_dpp v49, v47 quad_perm:[2,3,0,1] row_mask:0xf bank_mask:0xf
	v_mov_b32_dpp v52, v50 quad_perm:[2,3,0,1] row_mask:0xf bank_mask:0xf
	v_mov_b32_dpp v53, v51 quad_perm:[2,3,0,1] row_mask:0xf bank_mask:0xf
	v_mov_b32_dpp v56, v54 quad_perm:[2,3,0,1] row_mask:0xf bank_mask:0xf
	v_mov_b32_dpp v57, v55 quad_perm:[2,3,0,1] row_mask:0xf bank_mask:0xf
	s_and_saveexec_b64 s[4:5], s[0:1]
	s_cbranch_execz .LBB0_1119
	s_waitcnt lgkmcnt(6)
	v_pk_add_f32 v[58:59], v[38:39], v[42:43]
	s_waitcnt lgkmcnt(4)
	v_pk_add_f32 v[60:61], v[46:47], v[48:49]
	s_waitcnt lgkmcnt(2)
	v_pk_add_f32 v[46:47], v[50:51], v[52:53]
	s_waitcnt lgkmcnt(0)
	v_pk_add_f32 v[48:49], v[54:55], v[56:57]
	ds_write_b128 v231, v[58:61] offset:512
	ds_write_b128 v231, v[46:49] offset:640
.LBB0_1119:
	s_or_b64 exec, exec, s[4:5]
	v_mov_b32_e32 v191, v190
	v_pk_mul_f32 v[50:51], v[118:119], v[190:191]
	v_pk_mul_f32 v[38:39], v[102:103], v[190:191]
	v_pk_mul_f32 v[54:55], v[120:121], v[190:191]
	s_waitcnt lgkmcnt(6)
	v_pk_mul_f32 v[42:43], v[104:105], v[190:191]
	v_mov_b32_dpp v46, v50 quad_perm:[1,0,3,2] row_mask:0xf bank_mask:0xf
	v_mov_b32_dpp v47, v51 quad_perm:[1,0,3,2] row_mask:0xf bank_mask:0xf
	s_waitcnt lgkmcnt(5)
	v_mov_b32_dpp v52, v54 quad_perm:[1,0,3,2] row_mask:0xf bank_mask:0xf
	s_waitcnt lgkmcnt(5)
	v_mov_b32_dpp v53, v55 quad_perm:[1,0,3,2] row_mask:0xf bank_mask:0xf
	v_mov_b32_dpp v58, v38 quad_perm:[1,0,3,2] row_mask:0xf bank_mask:0xf
	v_mov_b32_dpp v59, v39 quad_perm:[1,0,3,2] row_mask:0xf bank_mask:0xf
	v_mov_b32_dpp v62, v42 quad_perm:[1,0,3,2] row_mask:0xf bank_mask:0xf
	v_mov_b32_dpp v63, v43 quad_perm:[1,0,3,2] row_mask:0xf bank_mask:0xf
	s_waitcnt lgkmcnt(6)
	v_pk_fma_f32 v[46:47], v[118:119], v[190:191], v[46:47]
	s_waitcnt lgkmcnt(4)
	v_pk_fma_f32 v[52:53], v[120:121], v[190:191], v[52:53]
	s_waitcnt lgkmcnt(2)
	v_pk_fma_f32 v[58:59], v[102:103], v[190:191], v[58:59]
	v_mov_b32_dpp v48, v46 quad_perm:[2,3,0,1] row_mask:0xf bank_mask:0xf
	s_waitcnt lgkmcnt(1)
	v_pk_fma_f32 v[62:63], v[104:105], v[190:191], v[62:63]
	v_mov_b32_dpp v49, v47 quad_perm:[2,3,0,1] row_mask:0xf bank_mask:0xf
	v_mov_b32_dpp v56, v52 quad_perm:[2,3,0,1] row_mask:0xf bank_mask:0xf
	v_mov_b32_dpp v57, v53 quad_perm:[2,3,0,1] row_mask:0xf bank_mask:0xf
	v_mov_b32_dpp v60, v58 quad_perm:[2,3,0,1] row_mask:0xf bank_mask:0xf
	v_mov_b32_dpp v61, v59 quad_perm:[2,3,0,1] row_mask:0xf bank_mask:0xf
	v_mov_b32_dpp v64, v62 quad_perm:[2,3,0,1] row_mask:0xf bank_mask:0xf
	v_mov_b32_dpp v65, v63 quad_perm:[2,3,0,1] row_mask:0xf bank_mask:0xf
	s_and_saveexec_b64 s[4:5], s[0:1]
	s_cbranch_execz .LBB0_1121
	s_waitcnt lgkmcnt(6)
	v_pk_add_f32 v[46:47], v[46:47], v[48:49]
	s_waitcnt lgkmcnt(4)
	v_pk_add_f32 v[48:49], v[52:53], v[56:57]
	ds_write_b128 v231, v[46:49] offset:544
	s_waitcnt lgkmcnt(3)
	v_pk_add_f32 v[46:47], v[58:59], v[60:61]
	s_waitcnt lgkmcnt(1)
	v_pk_add_f32 v[48:49], v[62:63], v[64:65]
	ds_write_b128 v231, v[46:49] offset:672
.LBB0_1121:
	s_or_b64 exec, exec, s[4:5]
	v_pk_mul_f32 v[52:53], v[122:123], v[190:191]
	v_pk_mul_f32 v[46:47], v[106:107], v[190:191]
	s_waitcnt lgkmcnt(4)
	v_pk_mul_f32 v[56:57], v[124:125], v[190:191]
	v_pk_mul_f32 v[48:49], v[108:109], v[190:191]
	v_mov_b32_dpp v58, v52 quad_perm:[1,0,3,2] row_mask:0xf bank_mask:0xf
	v_mov_b32_dpp v59, v53 quad_perm:[1,0,3,2] row_mask:0xf bank_mask:0xf
	v_mov_b32_dpp v62, v56 quad_perm:[1,0,3,2] row_mask:0xf bank_mask:0xf
	v_mov_b32_dpp v63, v57 quad_perm:[1,0,3,2] row_mask:0xf bank_mask:0xf
	v_mov_b32_dpp v98, v46 quad_perm:[1,0,3,2] row_mask:0xf bank_mask:0xf
	v_mov_b32_dpp v99, v47 quad_perm:[1,0,3,2] row_mask:0xf bank_mask:0xf
	v_mov_b32_dpp v102, v48 quad_perm:[1,0,3,2] row_mask:0xf bank_mask:0xf
	v_mov_b32_dpp v103, v49 quad_perm:[1,0,3,2] row_mask:0xf bank_mask:0xf
	s_waitcnt lgkmcnt(6)
	v_pk_fma_f32 v[58:59], v[122:123], v[190:191], v[58:59]
	s_waitcnt lgkmcnt(4)
	v_pk_fma_f32 v[62:63], v[124:125], v[190:191], v[62:63]
	s_waitcnt lgkmcnt(2)
	v_pk_fma_f32 v[98:99], v[106:107], v[190:191], v[98:99]
	v_mov_b32_dpp v60, v58 quad_perm:[2,3,0,1] row_mask:0xf bank_mask:0xf
	s_waitcnt lgkmcnt(1)
	v_pk_fma_f32 v[102:103], v[108:109], v[190:191], v[102:103]
	v_mov_b32_dpp v61, v59 quad_perm:[2,3,0,1] row_mask:0xf bank_mask:0xf
	v_mov_b32_dpp v64, v62 quad_perm:[2,3,0,1] row_mask:0xf bank_mask:0xf
	v_mov_b32_dpp v65, v63 quad_perm:[2,3,0,1] row_mask:0xf bank_mask:0xf
	v_mov_b32_dpp v100, v98 quad_perm:[2,3,0,1] row_mask:0xf bank_mask:0xf
	v_mov_b32_dpp v101, v99 quad_perm:[2,3,0,1] row_mask:0xf bank_mask:0xf
	v_mov_b32_dpp v104, v102 quad_perm:[2,3,0,1] row_mask:0xf bank_mask:0xf
	v_mov_b32_dpp v105, v103 quad_perm:[2,3,0,1] row_mask:0xf bank_mask:0xf
	s_and_saveexec_b64 s[4:5], s[0:1]
	s_cbranch_execz .LBB0_1123
	s_waitcnt lgkmcnt(6)
	v_pk_add_f32 v[58:59], v[58:59], v[60:61]
	s_waitcnt lgkmcnt(4)
	v_pk_add_f32 v[60:61], v[62:63], v[64:65]
	ds_write_b128 v231, v[58:61] offset:576
	s_waitcnt lgkmcnt(3)
	v_pk_add_f32 v[58:59], v[98:99], v[100:101]
	s_waitcnt lgkmcnt(1)
	v_pk_add_f32 v[60:61], v[102:103], v[104:105]
	ds_write_b128 v231, v[58:61] offset:704
.LBB0_1123:
	s_or_b64 exec, exec, s[4:5]
	v_pk_mul_f32 v[62:63], v[126:127], v[190:191]
	v_pk_mul_f32 v[58:59], v[110:111], v[190:191]
	s_waitcnt lgkmcnt(4)
	v_pk_mul_f32 v[64:65], v[128:129], v[190:191]
	v_pk_mul_f32 v[60:61], v[112:113], v[190:191]
	v_mov_b32_dpp v98, v62 quad_perm:[1,0,3,2] row_mask:0xf bank_mask:0xf
	v_mov_b32_dpp v99, v63 quad_perm:[1,0,3,2] row_mask:0xf bank_mask:0xf
	v_mov_b32_dpp v102, v64 quad_perm:[1,0,3,2] row_mask:0xf bank_mask:0xf
	v_mov_b32_dpp v103, v65 quad_perm:[1,0,3,2] row_mask:0xf bank_mask:0xf
	v_mov_b32_dpp v106, v58 quad_perm:[1,0,3,2] row_mask:0xf bank_mask:0xf
	v_mov_b32_dpp v107, v59 quad_perm:[1,0,3,2] row_mask:0xf bank_mask:0xf
	v_mov_b32_dpp v114, v60 quad_perm:[1,0,3,2] row_mask:0xf bank_mask:0xf
	v_mov_b32_dpp v115, v61 quad_perm:[1,0,3,2] row_mask:0xf bank_mask:0xf
	s_waitcnt lgkmcnt(6)
	v_pk_fma_f32 v[98:99], v[126:127], v[190:191], v[98:99]
	s_waitcnt lgkmcnt(4)
	v_pk_fma_f32 v[102:103], v[128:129], v[190:191], v[102:103]
	s_waitcnt lgkmcnt(2)
	v_pk_fma_f32 v[106:107], v[110:111], v[190:191], v[106:107]
	v_mov_b32_dpp v100, v98 quad_perm:[2,3,0,1] row_mask:0xf bank_mask:0xf
	s_waitcnt lgkmcnt(1)
	v_pk_fma_f32 v[110:111], v[112:113], v[190:191], v[114:115]
	v_mov_b32_dpp v101, v99 quad_perm:[2,3,0,1] row_mask:0xf bank_mask:0xf
	v_mov_b32_dpp v104, v102 quad_perm:[2,3,0,1] row_mask:0xf bank_mask:0xf
	v_mov_b32_dpp v105, v103 quad_perm:[2,3,0,1] row_mask:0xf bank_mask:0xf
	v_mov_b32_dpp v108, v106 quad_perm:[2,3,0,1] row_mask:0xf bank_mask:0xf
	v_mov_b32_dpp v109, v107 quad_perm:[2,3,0,1] row_mask:0xf bank_mask:0xf
	v_mov_b32_dpp v112, v110 quad_perm:[2,3,0,1] row_mask:0xf bank_mask:0xf
	v_mov_b32_dpp v113, v111 quad_perm:[2,3,0,1] row_mask:0xf bank_mask:0xf
	s_and_saveexec_b64 s[4:5], s[0:1]
	s_cbranch_execz .LBB0_1125
	s_waitcnt lgkmcnt(6)
	v_pk_add_f32 v[98:99], v[98:99], v[100:101]
	s_waitcnt lgkmcnt(4)
	v_pk_add_f32 v[100:101], v[102:103], v[104:105]
	ds_write_b128 v231, v[98:101] offset:608
	s_waitcnt lgkmcnt(3)
	v_pk_add_f32 v[98:99], v[106:107], v[108:109]
	s_waitcnt lgkmcnt(1)
	v_pk_add_f32 v[100:101], v[110:111], v[112:113]
	ds_write_b128 v231, v[98:101] offset:736

.LBB0_1130:
	v_pk_mul_f32 v[40:41], v[82:83], v[190:191] op_sel_hi:[1,0]
	v_pk_mul_f32 v[34:35], v[66:67], v[190:191] op_sel_hi:[1,0]
	v_pk_mul_f32 v[44:45], v[84:85], v[190:191] op_sel_hi:[1,0]
	v_pk_mul_f32 v[36:37], v[68:69], v[190:191] op_sel_hi:[1,0]
	v_mov_b32_dpp v38, v40 quad_perm:[1,0,3,2] row_mask:0xf bank_mask:0xf
	v_mov_b32_dpp v39, v41 quad_perm:[1,0,3,2] row_mask:0xf bank_mask:0xf
	v_mov_b32_dpp v46, v44 quad_perm:[1,0,3,2] row_mask:0xf bank_mask:0xf
	v_mov_b32_dpp v47, v45 quad_perm:[1,0,3,2] row_mask:0xf bank_mask:0xf
	v_mov_b32_dpp v50, v34 quad_perm:[1,0,3,2] row_mask:0xf bank_mask:0xf
	v_mov_b32_dpp v51, v35 quad_perm:[1,0,3,2] row_mask:0xf bank_mask:0xf
	v_mov_b32_dpp v54, v36 quad_perm:[1,0,3,2] row_mask:0xf bank_mask:0xf
	v_mov_b32_dpp v55, v37 quad_perm:[1,0,3,2] row_mask:0xf bank_mask:0xf
	s_waitcnt lgkmcnt(6)
	v_pk_fma_f32 v[38:39], v[82:83], v[190:191], v[38:39] op_sel_hi:[1,0,1]
	s_waitcnt lgkmcnt(4)
	v_pk_fma_f32 v[46:47], v[84:85], v[190:191], v[46:47] op_sel_hi:[1,0,1]
	s_waitcnt lgkmcnt(2)
	v_pk_fma_f32 v[50:51], v[66:67], v[190:191], v[50:51] op_sel_hi:[1,0,1]
	v_mov_b32_dpp v42, v38 quad_perm:[2,3,0,1] row_mask:0xf bank_mask:0xf
	s_waitcnt lgkmcnt(1)
	v_pk_fma_f32 v[54:55], v[68:69], v[190:191], v[54:55] op_sel_hi:[1,0,1]
	v_mov_b32_dpp v43, v39 quad_perm:[2,3,0,1] row_mask:0xf bank_mask:0xf
	v_mov_b32_dpp v48, v46 quad_perm:[2,3,0,1] row_mask:0xf bank_mask:0xf
	v_mov_b32_dpp v49, v47 quad_perm:[2,3,0,1] row_mask:0xf bank_mask:0xf
	v_mov_b32_dpp v52, v50 quad_perm:[2,3,0,1] row_mask:0xf bank_mask:0xf
	v_mov_b32_dpp v53, v51 quad_perm:[2,3,0,1] row_mask:0xf bank_mask:0xf
	v_mov_b32_dpp v56, v54 quad_perm:[2,3,0,1] row_mask:0xf bank_mask:0xf
	v_mov_b32_dpp v57, v55 quad_perm:[2,3,0,1] row_mask:0xf bank_mask:0xf
	s_and_saveexec_b64 s[2:3], s[0:1]
	s_cbranch_execz .LBB0_1132
	s_waitcnt lgkmcnt(6)
	v_pk_add_f32 v[58:59], v[38:39], v[42:43]
	s_waitcnt lgkmcnt(4)
	v_pk_add_f32 v[60:61], v[46:47], v[48:49]
	s_waitcnt lgkmcnt(2)
	v_pk_add_f32 v[46:47], v[50:51], v[52:53]
	s_waitcnt lgkmcnt(0)
	v_pk_add_f32 v[48:49], v[54:55], v[56:57]
	ds_write_b128 v231, v[58:61] offset:768
	ds_write_b128 v231, v[46:49] offset:896
.LBB0_1132:
	s_or_b64 exec, exec, s[2:3]
	v_mov_b32_e32 v191, v190
	v_pk_mul_f32 v[50:51], v[86:87], v[190:191]
	v_pk_mul_f32 v[38:39], v[70:71], v[190:191]
	v_pk_mul_f32 v[54:55], v[88:89], v[190:191]
	s_waitcnt lgkmcnt(6)
	v_pk_mul_f32 v[42:43], v[72:73], v[190:191]
	v_mov_b32_dpp v46, v50 quad_perm:[1,0,3,2] row_mask:0xf bank_mask:0xf
	v_mov_b32_dpp v47, v51 quad_perm:[1,0,3,2] row_mask:0xf bank_mask:0xf
	s_waitcnt lgkmcnt(5)
	v_mov_b32_dpp v52, v54 quad_perm:[1,0,3,2] row_mask:0xf bank_mask:0xf
	s_waitcnt lgkmcnt(5)
	v_mov_b32_dpp v53, v55 quad_perm:[1,0,3,2] row_mask:0xf bank_mask:0xf
	v_mov_b32_dpp v58, v38 quad_perm:[1,0,3,2] row_mask:0xf bank_mask:0xf
	v_mov_b32_dpp v59, v39 quad_perm:[1,0,3,2] row_mask:0xf bank_mask:0xf
	v_mov_b32_dpp v62, v42 quad_perm:[1,0,3,2] row_mask:0xf bank_mask:0xf
	v_mov_b32_dpp v63, v43 quad_perm:[1,0,3,2] row_mask:0xf bank_mask:0xf
	s_waitcnt lgkmcnt(6)
	v_pk_fma_f32 v[46:47], v[86:87], v[190:191], v[46:47]
	s_waitcnt lgkmcnt(4)
	v_pk_fma_f32 v[52:53], v[88:89], v[190:191], v[52:53]
	s_waitcnt lgkmcnt(2)
	v_pk_fma_f32 v[58:59], v[70:71], v[190:191], v[58:59]
	v_mov_b32_dpp v48, v46 quad_perm:[2,3,0,1] row_mask:0xf bank_mask:0xf
	s_waitcnt lgkmcnt(1)
	v_pk_fma_f32 v[62:63], v[72:73], v[190:191], v[62:63]
	v_mov_b32_dpp v49, v47 quad_perm:[2,3,0,1] row_mask:0xf bank_mask:0xf
	v_mov_b32_dpp v56, v52 quad_perm:[2,3,0,1] row_mask:0xf bank_mask:0xf
	v_mov_b32_dpp v57, v53 quad_perm:[2,3,0,1] row_mask:0xf bank_mask:0xf
	v_mov_b32_dpp v60, v58 quad_perm:[2,3,0,1] row_mask:0xf bank_mask:0xf
	v_mov_b32_dpp v61, v59 quad_perm:[2,3,0,1] row_mask:0xf bank_mask:0xf
	v_mov_b32_dpp v64, v62 quad_perm:[2,3,0,1] row_mask:0xf bank_mask:0xf
	v_mov_b32_dpp v65, v63 quad_perm:[2,3,0,1] row_mask:0xf bank_mask:0xf
	s_and_saveexec_b64 s[2:3], s[0:1]
	s_cbranch_execz .LBB0_1134
	s_waitcnt lgkmcnt(6)
	v_pk_add_f32 v[46:47], v[46:47], v[48:49]
	s_waitcnt lgkmcnt(4)
	v_pk_add_f32 v[48:49], v[52:53], v[56:57]
	ds_write_b128 v231, v[46:49] offset:800
	s_waitcnt lgkmcnt(3)
	v_pk_add_f32 v[46:47], v[58:59], v[60:61]
	s_waitcnt lgkmcnt(1)
	v_pk_add_f32 v[48:49], v[62:63], v[64:65]
	ds_write_b128 v231, v[46:49] offset:928
.LBB0_1134:
	s_or_b64 exec, exec, s[2:3]
	v_pk_mul_f32 v[52:53], v[90:91], v[190:191]
	v_pk_mul_f32 v[46:47], v[74:75], v[190:191]
	s_waitcnt lgkmcnt(4)
	v_pk_mul_f32 v[56:57], v[92:93], v[190:191]
	v_pk_mul_f32 v[48:49], v[76:77], v[190:191]
	v_mov_b32_dpp v58, v52 quad_perm:[1,0,3,2] row_mask:0xf bank_mask:0xf
	v_mov_b32_dpp v59, v53 quad_perm:[1,0,3,2] row_mask:0xf bank_mask:0xf
	v_mov_b32_dpp v62, v56 quad_perm:[1,0,3,2] row_mask:0xf bank_mask:0xf
	v_mov_b32_dpp v63, v57 quad_perm:[1,0,3,2] row_mask:0xf bank_mask:0xf
	v_mov_b32_dpp v66, v46 quad_perm:[1,0,3,2] row_mask:0xf bank_mask:0xf
	v_mov_b32_dpp v67, v47 quad_perm:[1,0,3,2] row_mask:0xf bank_mask:0xf
	v_mov_b32_dpp v70, v48 quad_perm:[1,0,3,2] row_mask:0xf bank_mask:0xf
	v_mov_b32_dpp v71, v49 quad_perm:[1,0,3,2] row_mask:0xf bank_mask:0xf
	s_waitcnt lgkmcnt(6)
	v_pk_fma_f32 v[58:59], v[90:91], v[190:191], v[58:59]
	s_waitcnt lgkmcnt(4)
	v_pk_fma_f32 v[62:63], v[92:93], v[190:191], v[62:63]
	s_waitcnt lgkmcnt(2)
	v_pk_fma_f32 v[66:67], v[74:75], v[190:191], v[66:67]
	v_mov_b32_dpp v60, v58 quad_perm:[2,3,0,1] row_mask:0xf bank_mask:0xf
	s_waitcnt lgkmcnt(1)
	v_pk_fma_f32 v[70:71], v[76:77], v[190:191], v[70:71]
	v_mov_b32_dpp v61, v59 quad_perm:[2,3,0,1] row_mask:0xf bank_mask:0xf
	v_mov_b32_dpp v64, v62 quad_perm:[2,3,0,1] row_mask:0xf bank_mask:0xf
	v_mov_b32_dpp v65, v63 quad_perm:[2,3,0,1] row_mask:0xf bank_mask:0xf
	v_mov_b32_dpp v68, v66 quad_perm:[2,3,0,1] row_mask:0xf bank_mask:0xf
	v_mov_b32_dpp v69, v67 quad_perm:[2,3,0,1] row_mask:0xf bank_mask:0xf
	v_mov_b32_dpp v72, v70 quad_perm:[2,3,0,1] row_mask:0xf bank_mask:0xf
	v_mov_b32_dpp v73, v71 quad_perm:[2,3,0,1] row_mask:0xf bank_mask:0xf
	s_and_saveexec_b64 s[2:3], s[0:1]
	s_cbranch_execz .LBB0_1136
	s_waitcnt lgkmcnt(6)
	v_pk_add_f32 v[58:59], v[58:59], v[60:61]
	s_waitcnt lgkmcnt(4)
	v_pk_add_f32 v[60:61], v[62:63], v[64:65]
	ds_write_b128 v231, v[58:61] offset:832
	s_waitcnt lgkmcnt(3)
	v_pk_add_f32 v[58:59], v[66:67], v[68:69]
	s_waitcnt lgkmcnt(1)
	v_pk_add_f32 v[60:61], v[70:71], v[72:73]
	ds_write_b128 v231, v[58:61] offset:960
.LBB0_1136:
	s_or_b64 exec, exec, s[2:3]
	v_pk_mul_f32 v[62:63], v[94:95], v[190:191]
	v_pk_mul_f32 v[58:59], v[78:79], v[190:191]
	s_waitcnt lgkmcnt(4)
	v_pk_mul_f32 v[64:65], v[96:97], v[190:191]
	v_pk_mul_f32 v[60:61], v[80:81], v[190:191]
	v_mov_b32_dpp v66, v62 quad_perm:[1,0,3,2] row_mask:0xf bank_mask:0xf
	v_mov_b32_dpp v67, v63 quad_perm:[1,0,3,2] row_mask:0xf bank_mask:0xf
	v_mov_b32_dpp v70, v64 quad_perm:[1,0,3,2] row_mask:0xf bank_mask:0xf
	v_mov_b32_dpp v71, v65 quad_perm:[1,0,3,2] row_mask:0xf bank_mask:0xf
	v_mov_b32_dpp v74, v58 quad_perm:[1,0,3,2] row_mask:0xf bank_mask:0xf
	v_mov_b32_dpp v75, v59 quad_perm:[1,0,3,2] row_mask:0xf bank_mask:0xf
	v_mov_b32_dpp v82, v60 quad_perm:[1,0,3,2] row_mask:0xf bank_mask:0xf
	v_mov_b32_dpp v83, v61 quad_perm:[1,0,3,2] row_mask:0xf bank_mask:0xf
	s_waitcnt lgkmcnt(6)
	v_pk_fma_f32 v[66:67], v[94:95], v[190:191], v[66:67]
	s_waitcnt lgkmcnt(4)
	v_pk_fma_f32 v[70:71], v[96:97], v[190:191], v[70:71]
	s_waitcnt lgkmcnt(2)
	v_pk_fma_f32 v[74:75], v[78:79], v[190:191], v[74:75]
	v_mov_b32_dpp v68, v66 quad_perm:[2,3,0,1] row_mask:0xf bank_mask:0xf
	s_waitcnt lgkmcnt(1)
	v_pk_fma_f32 v[78:79], v[80:81], v[190:191], v[82:83]
	v_mov_b32_dpp v69, v67 quad_perm:[2,3,0,1] row_mask:0xf bank_mask:0xf
	v_mov_b32_dpp v72, v70 quad_perm:[2,3,0,1] row_mask:0xf bank_mask:0xf
	v_mov_b32_dpp v73, v71 quad_perm:[2,3,0,1] row_mask:0xf bank_mask:0xf
	v_mov_b32_dpp v76, v74 quad_perm:[2,3,0,1] row_mask:0xf bank_mask:0xf
	v_mov_b32_dpp v77, v75 quad_perm:[2,3,0,1] row_mask:0xf bank_mask:0xf
	v_mov_b32_dpp v80, v78 quad_perm:[2,3,0,1] row_mask:0xf bank_mask:0xf
	v_mov_b32_dpp v81, v79 quad_perm:[2,3,0,1] row_mask:0xf bank_mask:0xf
	s_and_saveexec_b64 s[2:3], s[0:1]
	s_cbranch_execz .LBB0_1138
	s_waitcnt lgkmcnt(6)
	v_pk_add_f32 v[66:67], v[66:67], v[68:69]
	s_waitcnt lgkmcnt(4)
	v_pk_add_f32 v[68:69], v[70:71], v[72:73]
	ds_write_b128 v231, v[66:69] offset:864
	s_waitcnt lgkmcnt(3)
	v_pk_add_f32 v[66:67], v[74:75], v[76:77]
	s_waitcnt lgkmcnt(1)
	v_pk_add_f32 v[68:69], v[78:79], v[80:81]
	ds_write_b128 v231, v[66:69] offset:992

.LBB0_1145:
	s_or_b64 exec, exec, s[8:9]
	v_and_b32_e32 v34, 0xffffffc0, v37
	v_add_u32_e32 v34, v34, v40
	v_cndmask_b32_e64 v34, v34, v39, s[0:1]
	v_cndmask_b32_e64 v47, v34, v41, s[6:7]
	ds_write_b32 v43, v47
	ds_read_b128 v[60:63], v42
	ds_read_b128 v[64:67], v42 offset:16
	ds_read_b128 v[68:71], v42 offset:32
	ds_read_b128 v[72:75], v42 offset:48
	ds_read_b128 v[76:79], v42 offset:64
	ds_read_b128 v[80:83], v42 offset:80
	ds_read_b128 v[84:87], v42 offset:96
	ds_read_b128 v[88:91], v42 offset:112
	v_mov_b32_e32 v34, 0
	v_mov_b32_e32 v35, 0
	s_waitcnt lgkmcnt(7)
	ds_read_b128 v[92:95], v42 offset:128
	ds_read_b128 v[96:99], v42 offset:144
	ds_read_b128 v[100:103], v42 offset:160
	ds_read_b128 v[104:107], v42 offset:176
	ds_read_b128 v[108:111], v42 offset:192
	ds_read_b128 v[112:115], v42 offset:208
	ds_read_b128 v[120:123], v42 offset:224
	ds_read_b128 v[124:127], v42 offset:240
	v_cmp_gt_u32_e64 s[14:15], v60, v47
	v_cmp_gt_u32_e64 s[8:9], v61, v47
	v_cmp_gt_u32_e64 s[10:11], v62, v47
	v_addc_co_u32_e64 v34, s[14:15], 0, v34, s[14:15]
	v_cmp_gt_u32_e64 s[14:15], v63, v47
	v_addc_co_u32_e64 v35, s[8:9], 0, v35, s[8:9]
	s_waitcnt lgkmcnt(14)
	v_cmp_gt_u32_e64 s[8:9], v64, v47
	v_addc_co_u32_e64 v34, s[10:11], 0, v34, s[10:11]
	v_cmp_gt_u32_e64 s[10:11], v65, v47
	v_addc_co_u32_e64 v35, s[14:15], 0, v35, s[14:15]
	v_cmp_gt_u32_e64 s[14:15], v66, v47
	v_addc_co_u32_e64 v34, s[8:9], 0, v34, s[8:9]
	v_cmp_gt_u32_e64 s[8:9], v67, v47
	v_addc_co_u32_e64 v35, s[10:11], 0, v35, s[10:11]
	s_waitcnt lgkmcnt(13)
	v_cmp_gt_u32_e64 s[10:11], v68, v47
	v_addc_co_u32_e64 v34, s[14:15], 0, v34, s[14:15]
	v_cmp_gt_u32_e64 s[14:15], v69, v47
	v_addc_co_u32_e64 v35, s[8:9], 0, v35, s[8:9]
	v_cmp_gt_u32_e64 s[8:9], v70, v47
	v_addc_co_u32_e64 v34, s[10:11], 0, v34, s[10:11]
	v_cmp_gt_u32_e64 s[10:11], v71, v47
	v_addc_co_u32_e64 v35, s[14:15], 0, v35, s[14:15]
	s_waitcnt lgkmcnt(12)
	v_cmp_gt_u32_e64 s[14:15], v72, v47
	v_addc_co_u32_e64 v34, s[8:9], 0, v34, s[8:9]
	v_cmp_gt_u32_e64 s[8:9], v73, v47
	v_addc_co_u32_e64 v35, s[10:11], 0, v35, s[10:11]
	v_cmp_gt_u32_e64 s[10:11], v74, v47
	v_addc_co_u32_e64 v34, s[14:15], 0, v34, s[14:15]
	v_cmp_gt_u32_e64 s[14:15], v75, v47
	v_addc_co_u32_e64 v35, s[8:9], 0, v35, s[8:9]
	s_waitcnt lgkmcnt(11)
	v_cmp_gt_u32_e64 s[8:9], v76, v47
	v_addc_co_u32_e64 v34, s[10:11], 0, v34, s[10:11]
	v_cmp_gt_u32_e64 s[10:11], v77, v47
	v_addc_co_u32_e64 v35, s[14:15], 0, v35, s[14:15]
	v_cmp_gt_u32_e64 s[14:15], v78, v47
	v_addc_co_u32_e64 v34, s[8:9], 0, v34, s[8:9]
	v_cmp_gt_u32_e64 s[8:9], v79, v47
	v_addc_co_u32_e64 v35, s[10:11], 0, v35, s[10:11]
	s_waitcnt lgkmcnt(10)
	v_cmp_gt_u32_e64 s[10:11], v80, v47
	v_addc_co_u32_e64 v34, s[14:15], 0, v34, s[14:15]
	v_cmp_gt_u32_e64 s[14:15], v81, v47
	v_addc_co_u32_e64 v35, s[8:9], 0, v35, s[8:9]
	v_cmp_gt_u32_e64 s[8:9], v82, v47
	v_addc_co_u32_e64 v34, s[10:11], 0, v34, s[10:11]
	v_cmp_gt_u32_e64 s[10:11], v83, v47
	v_addc_co_u32_e64 v35, s[14:15], 0, v35, s[14:15]
	s_waitcnt lgkmcnt(9)
	v_cmp_gt_u32_e64 s[14:15], v84, v47
	v_addc_co_u32_e64 v34, s[8:9], 0, v34, s[8:9]
	v_cmp_gt_u32_e64 s[8:9], v85, v47
	v_addc_co_u32_e64 v35, s[10:11], 0, v35, s[10:11]
	v_cmp_gt_u32_e64 s[10:11], v86, v47
	v_addc_co_u32_e64 v34, s[14:15], 0, v34, s[14:15]
	v_cmp_gt_u32_e64 s[14:15], v87, v47
	v_addc_co_u32_e64 v35, s[8:9], 0, v35, s[8:9]
	s_waitcnt lgkmcnt(8)
	v_cmp_gt_u32_e64 s[8:9], v88, v47
	v_addc_co_u32_e64 v34, s[10:11], 0, v34, s[10:11]
	v_cmp_gt_u32_e64 s[10:11], v89, v47
	v_addc_co_u32_e64 v35, s[14:15], 0, v35, s[14:15]
	v_cmp_gt_u32_e64 s[14:15], v90, v47
	v_addc_co_u32_e64 v34, s[8:9], 0, v34, s[8:9]
	v_cmp_gt_u32_e64 s[8:9], v91, v47
	v_addc_co_u32_e64 v35, s[10:11], 0, v35, s[10:11]
	s_waitcnt lgkmcnt(7)
	v_cmp_gt_u32_e64 s[10:11], v92, v47
	v_addc_co_u32_e64 v34, s[14:15], 0, v34, s[14:15]
	v_cmp_gt_u32_e64 s[14:15], v93, v47
	v_addc_co_u32_e64 v35, s[8:9], 0, v35, s[8:9]
	v_cmp_gt_u32_e64 s[8:9], v94, v47
	v_addc_co_u32_e64 v34, s[10:11], 0, v34, s[10:11]
	v_cmp_gt_u32_e64 s[10:11], v95, v47
	v_addc_co_u32_e64 v35, s[14:15], 0, v35, s[14:15]
	s_waitcnt lgkmcnt(6)
	v_cmp_gt_u32_e64 s[14:15], v96, v47
	v_addc_co_u32_e64 v34, s[8:9], 0, v34, s[8:9]
	v_cmp_gt_u32_e64 s[8:9], v97, v47
	v_addc_co_u32_e64 v35, s[10:11], 0, v35, s[10:11]
	v_cmp_gt_u32_e64 s[10:11], v98, v47
	v_addc_co_u32_e64 v34, s[14:15], 0, v34, s[14:15]
	v_cmp_gt_u32_e64 s[14:15], v99, v47
	v_addc_co_u32_e64 v35, s[8:9], 0, v35, s[8:9]
	s_waitcnt lgkmcnt(5)
	v_cmp_gt_u32_e64 s[8:9], v100, v47
	v_addc_co_u32_e64 v34, s[10:11], 0, v34, s[10:11]
	v_cmp_gt_u32_e64 s[10:11], v101, v47
	v_addc_co_u32_e64 v35, s[14:15], 0, v35, s[14:15]
	v_cmp_gt_u32_e64 s[14:15], v102, v47
	v_addc_co_u32_e64 v34, s[8:9], 0, v34, s[8:9]
	v_cmp_gt_u32_e64 s[8:9], v103, v47
	v_addc_co_u32_e64 v35, s[10:11], 0, v35, s[10:11]
	s_waitcnt lgkmcnt(4)
	v_cmp_gt_u32_e64 s[10:11], v104, v47
	v_addc_co_u32_e64 v34, s[14:15], 0, v34, s[14:15]
	v_cmp_gt_u32_e64 s[14:15], v105, v47
	v_addc_co_u32_e64 v35, s[8:9], 0, v35, s[8:9]
	v_cmp_gt_u32_e64 s[8:9], v106, v47
	v_addc_co_u32_e64 v34, s[10:11], 0, v34, s[10:11]
	v_cmp_gt_u32_e64 s[10:11], v107, v47
	v_addc_co_u32_e64 v35, s[14:15], 0, v35, s[14:15]
	s_waitcnt lgkmcnt(3)
	v_cmp_gt_u32_e64 s[14:15], v108, v47
	v_addc_co_u32_e64 v34, s[8:9], 0, v34, s[8:9]
	v_cmp_gt_u32_e64 s[8:9], v109, v47
	v_addc_co_u32_e64 v35, s[10:11], 0, v35, s[10:11]
	v_cmp_gt_u32_e64 s[10:11], v110, v47
	v_addc_co_u32_e64 v34, s[14:15], 0, v34, s[14:15]
	v_cmp_gt_u32_e64 s[14:15], v111, v47
	v_addc_co_u32_e64 v35, s[8:9], 0, v35, s[8:9]
	s_waitcnt lgkmcnt(2)
	v_cmp_gt_u32_e64 s[8:9], v112, v47
	v_addc_co_u32_e64 v34, s[10:11], 0, v34, s[10:11]
	v_cmp_gt_u32_e64 s[10:11], v113, v47
	v_addc_co_u32_e64 v35, s[14:15], 0, v35, s[14:15]
	v_cmp_gt_u32_e64 s[14:15], v114, v47
	v_addc_co_u32_e64 v34, s[8:9], 0, v34, s[8:9]
	v_cmp_gt_u32_e64 s[8:9], v115, v47
	v_addc_co_u32_e64 v35, s[10:11], 0, v35, s[10:11]
	s_waitcnt lgkmcnt(1)
	v_cmp_gt_u32_e64 s[10:11], v120, v47
	v_addc_co_u32_e64 v34, s[14:15], 0, v34, s[14:15]
	v_cmp_gt_u32_e64 s[14:15], v121, v47
	v_addc_co_u32_e64 v35, s[8:9], 0, v35, s[8:9]
	v_cmp_gt_u32_e64 s[8:9], v122, v47
	v_addc_co_u32_e64 v34, s[10:11], 0, v34, s[10:11]
	v_cmp_gt_u32_e64 s[10:11], v123, v47
	v_addc_co_u32_e64 v35, s[14:15], 0, v35, s[14:15]
	s_waitcnt lgkmcnt(0)
	v_cmp_gt_u32_e64 s[14:15], v124, v47
	v_addc_co_u32_e64 v34, s[8:9], 0, v34, s[8:9]
	v_cmp_gt_u32_e64 s[8:9], v125, v47
	v_addc_co_u32_e64 v35, s[10:11], 0, v35, s[10:11]
	v_cmp_gt_u32_e64 s[10:11], v126, v47
	v_addc_co_u32_e64 v34, s[14:15], 0, v34, s[14:15]
	v_cmp_gt_u32_e64 s[14:15], v127, v47
	v_addc_co_u32_e64 v35, s[8:9], 0, v35, s[8:9]
	v_addc_co_u32_e64 v34, s[10:11], 0, v34, s[10:11]
	v_addc_co_u32_e64 v35, s[14:15], 0, v35, s[14:15]
	v_add_u32_e32 v34, v34, v35
	v_cmp_gt_u32_e64 s[10:11], 16, v34
	s_and_saveexec_b64 s[8:9], s[4:5]
	s_cbranch_execz .LBB0_1140
	v_add_u32_e32 v34, 0, v46
	v_mov_b64_e32 v[36:37], s[10:11]
	ds_write_b64 v34, v[36:37]
	s_branch .LBB0_1140
